# barrier: XCD leaders drop the unused XGEN increment and do not wait for their last counter increment; on top of flat release
# baseline (speedup 1.0000x reference)
; __device__ __forceinline__ unsigned xb_ld(unsigned* p)              { return __hip_atomic_load(p, __ATOMIC_RELAXED, __HIP_MEMORY_SCOPE_AGENT); }
; __device__ __forceinline__ unsigned xb_add(unsigned* p, unsigned v) { return __hip_atomic_fetch_add(p, v, __ATOMIC_RELAXED, __HIP_MEMORY_SCOPE_AGENT); }
; #define XB_SPIN(cond, bar) do { unsigned _sp = 0; while (cond) { __builtin_amdgcn_s_sleep(1); \
;     if ((++_sp & 255u) == 0u) { if (xb_ld(&(bar)[XB_TMO])) break; if (_sp > XB_SPIN_CAP) { atomicAdd(&(bar)[XB_TMO], 1u); break; } } } } while (0)
; __device__ __forceinline__ void xcd_barrier(const XcdBarrier& b) {
;     ...
;             __builtin_amdgcn_fence(__ATOMIC_RELEASE, "agent");
;             asm volatile("s_waitcnt vmcnt(0)" ::: "memory");
;             const unsigned og = xb_add(&bar[XB_TOP], 1u);
;             const unsigned tg = og / nx;
;             if (og + 1u == (tg + 1u) * nx) xb_add(&bar[XB_TOPGEN], 1u);
;             else XB_SPIN(xb_ld(&bar[XB_TOPGEN]) == tg, bar);
;             __builtin_amdgcn_fence(__ATOMIC_ACQUIRE, "agent");
;             xb_add(&bar[XB_XGEN(b.x)], 1u);
;             asm volatile("s_waitcnt vmcnt(0)" ::: "memory");
.LBB0_88:
	s_or_b64 exec, exec, s[10:11]
	s_mov_b64 s[10:11], exec
	v_mbcnt_lo_u32_b32 v1, s10, 0
	v_mbcnt_hi_u32_b32 v1, s11, v1
	v_cmp_eq_u32_e32 vcc, 0, v1
	s_nop 0
	buffer_inv sc1
	s_and_saveexec_b64 s[12:13], vcc
	s_cbranch_execz .LBB0_90
	s_bcnt1_i32_b64 s0, s[10:11]
	v_mov_b32_e32 v1, 0x2000
	v_mov_b32_e32 v2, s0
	s_nop 0
	s_nop 0
.LBB0_90:
	s_or_b64 exec, exec, s[12:13]
	s_nop 0

; __device__ __forceinline__ unsigned xb_ld(unsigned* p)              { return __hip_atomic_load(p, __ATOMIC_RELAXED, __HIP_MEMORY_SCOPE_AGENT); }
; __device__ __forceinline__ unsigned xb_add(unsigned* p, unsigned v) { return __hip_atomic_fetch_add(p, v, __ATOMIC_RELAXED, __HIP_MEMORY_SCOPE_AGENT); }
; #define XB_SPIN(cond, bar) do { unsigned _sp = 0; while (cond) { __builtin_amdgcn_s_sleep(1); \
;     if ((++_sp & 255u) == 0u) { if (xb_ld(&(bar)[XB_TMO])) break; if (_sp > XB_SPIN_CAP) { atomicAdd(&(bar)[XB_TMO], 1u); break; } } } } while (0)
; __device__ __forceinline__ void xcd_barrier(const XcdBarrier& b) {
;     ...
;             __builtin_amdgcn_fence(__ATOMIC_RELEASE, "agent");
;             asm volatile("s_waitcnt vmcnt(0)" ::: "memory");
;             const unsigned og = xb_add(&bar[XB_TOP], 1u);
;             const unsigned tg = og / nx;
;             if (og + 1u == (tg + 1u) * nx) xb_add(&bar[XB_TOPGEN], 1u);
;             else XB_SPIN(xb_ld(&bar[XB_TOPGEN]) == tg, bar);
;             __builtin_amdgcn_fence(__ATOMIC_ACQUIRE, "agent");
;             xb_add(&bar[XB_XGEN(b.x)], 1u);
;             asm volatile("s_waitcnt vmcnt(0)" ::: "memory");
.LBB0_638:
	s_or_b64 exec, exec, s[10:11]
	s_mov_b64 s[10:11], exec
	v_mbcnt_lo_u32_b32 v2, s10, 0
	v_mbcnt_hi_u32_b32 v2, s11, v2
	v_cmp_eq_u32_e32 vcc, 0, v2
	s_nop 0
	buffer_inv sc1
	s_and_saveexec_b64 s[12:13], vcc
	s_cbranch_execz .LBB0_640
	s_bcnt1_i32_b64 s0, s[10:11]
	v_mov_b32_e32 v2, 0x2000
	v_mov_b32_e32 v3, s0
	s_nop 0
	s_nop 0

; __device__ __forceinline__ unsigned xb_ld(unsigned* p)              { return __hip_atomic_load(p, __ATOMIC_RELAXED, __HIP_MEMORY_SCOPE_AGENT); }
; __device__ __forceinline__ unsigned xb_add(unsigned* p, unsigned v) { return __hip_atomic_fetch_add(p, v, __ATOMIC_RELAXED, __HIP_MEMORY_SCOPE_AGENT); }
; #define XB_SPIN(cond, bar) do { unsigned _sp = 0; while (cond) { __builtin_amdgcn_s_sleep(1); \
;     if ((++_sp & 255u) == 0u) { if (xb_ld(&(bar)[XB_TMO])) break; if (_sp > XB_SPIN_CAP) { atomicAdd(&(bar)[XB_TMO], 1u); break; } } } } while (0)
; __device__ __forceinline__ void xcd_barrier(const XcdBarrier& b) {
;     ...
;             __builtin_amdgcn_fence(__ATOMIC_RELEASE, "agent");
;             asm volatile("s_waitcnt vmcnt(0)" ::: "memory");
;             const unsigned og = xb_add(&bar[XB_TOP], 1u);
;             const unsigned tg = og / nx;
;             if (og + 1u == (tg + 1u) * nx) xb_add(&bar[XB_TOPGEN], 1u);
;             else XB_SPIN(xb_ld(&bar[XB_TOPGEN]) == tg, bar);
;             __builtin_amdgcn_fence(__ATOMIC_ACQUIRE, "agent");
;             xb_add(&bar[XB_XGEN(b.x)], 1u);
;             asm volatile("s_waitcnt vmcnt(0)" ::: "memory");
.LBB0_815:
	s_or_b64 exec, exec, s[12:13]
	s_mov_b64 s[12:13], exec
	v_mbcnt_lo_u32_b32 v2, s12, 0
	v_mbcnt_hi_u32_b32 v2, s13, v2
	v_cmp_eq_u32_e32 vcc, 0, v2
	s_nop 0
	buffer_inv sc1
	s_and_saveexec_b64 s[14:15], vcc
	s_cbranch_execz .LBB0_817
	s_bcnt1_i32_b64 s0, s[12:13]
	v_mov_b32_e32 v2, 0x2000
	v_mov_b32_e32 v3, s0
	s_nop 0
	s_nop 0
.LBB0_817:
	s_or_b64 exec, exec, s[14:15]
	s_nop 0

; __device__ __forceinline__ unsigned xb_ld(unsigned* p)              { return __hip_atomic_load(p, __ATOMIC_RELAXED, __HIP_MEMORY_SCOPE_AGENT); }
; __device__ __forceinline__ unsigned xb_add(unsigned* p, unsigned v) { return __hip_atomic_fetch_add(p, v, __ATOMIC_RELAXED, __HIP_MEMORY_SCOPE_AGENT); }
; #define XB_SPIN(cond, bar) do { unsigned _sp = 0; while (cond) { __builtin_amdgcn_s_sleep(1); \
;     if ((++_sp & 255u) == 0u) { if (xb_ld(&(bar)[XB_TMO])) break; if (_sp > XB_SPIN_CAP) { atomicAdd(&(bar)[XB_TMO], 1u); break; } } } } while (0)
; __device__ __forceinline__ void xcd_barrier(const XcdBarrier& b) {
;     ...
;             __builtin_amdgcn_fence(__ATOMIC_RELEASE, "agent");
;             asm volatile("s_waitcnt vmcnt(0)" ::: "memory");
;             const unsigned og = xb_add(&bar[XB_TOP], 1u);
;             const unsigned tg = og / nx;
;             if (og + 1u == (tg + 1u) * nx) xb_add(&bar[XB_TOPGEN], 1u);
;             else XB_SPIN(xb_ld(&bar[XB_TOPGEN]) == tg, bar);
;             __builtin_amdgcn_fence(__ATOMIC_ACQUIRE, "agent");
;             xb_add(&bar[XB_XGEN(b.x)], 1u);
;             asm volatile("s_waitcnt vmcnt(0)" ::: "memory");
.LBB0_1620:
	s_or_b64 exec, exec, s[8:9]
	s_mov_b64 s[8:9], exec
	v_mbcnt_lo_u32_b32 v2, s8, 0
	v_mbcnt_hi_u32_b32 v2, s9, v2
	v_cmp_eq_u32_e32 vcc, 0, v2
	s_nop 0
	buffer_inv sc1
	s_and_saveexec_b64 s[10:11], vcc
	s_cbranch_execz .LBB0_1622
	s_bcnt1_i32_b64 s3, s[8:9]
	v_mov_b32_e32 v2, 0x2000
	v_mov_b32_e32 v3, s3
	s_nop 0
	s_nop 0
.LBB0_1622:
	s_or_b64 exec, exec, s[10:11]
	s_nop 0

; __device__ __forceinline__ unsigned xb_ld(unsigned* p)              { return __hip_atomic_load(p, __ATOMIC_RELAXED, __HIP_MEMORY_SCOPE_AGENT); }
; __device__ __forceinline__ unsigned xb_add(unsigned* p, unsigned v) { return __hip_atomic_fetch_add(p, v, __ATOMIC_RELAXED, __HIP_MEMORY_SCOPE_AGENT); }
; #define XB_SPIN(cond, bar) do { unsigned _sp = 0; while (cond) { __builtin_amdgcn_s_sleep(1); \
;     if ((++_sp & 255u) == 0u) { if (xb_ld(&(bar)[XB_TMO])) break; if (_sp > XB_SPIN_CAP) { atomicAdd(&(bar)[XB_TMO], 1u); break; } } } } while (0)
; __device__ __forceinline__ void xcd_barrier(const XcdBarrier& b) {
;     ...
;             __builtin_amdgcn_fence(__ATOMIC_RELEASE, "agent");
;             asm volatile("s_waitcnt vmcnt(0)" ::: "memory");
;             const unsigned og = xb_add(&bar[XB_TOP], 1u);
;             const unsigned tg = og / nx;
;             if (og + 1u == (tg + 1u) * nx) xb_add(&bar[XB_TOPGEN], 1u);
;             else XB_SPIN(xb_ld(&bar[XB_TOPGEN]) == tg, bar);
;             __builtin_amdgcn_fence(__ATOMIC_ACQUIRE, "agent");
;             xb_add(&bar[XB_XGEN(b.x)], 1u);
;             asm volatile("s_waitcnt vmcnt(0)" ::: "memory");
.LBB0_2071:
	s_or_b64 exec, exec, s[8:9]
	s_mov_b64 s[8:9], exec
	v_mbcnt_lo_u32_b32 v1, s8, 0
	v_mbcnt_hi_u32_b32 v1, s9, v1
	v_cmp_eq_u32_e32 vcc, 0, v1
	s_nop 0
	buffer_inv sc1
	s_and_saveexec_b64 s[10:11], vcc
	s_cbranch_execz .LBB0_2073
	s_bcnt1_i32_b64 s3, s[8:9]
	v_mov_b32_e32 v1, 0x2000
	v_mov_b32_e32 v2, s3
	s_nop 0
	s_nop 0

; __device__ __forceinline__ unsigned xb_ld(unsigned* p)              { return __hip_atomic_load(p, __ATOMIC_RELAXED, __HIP_MEMORY_SCOPE_AGENT); }
; __device__ __forceinline__ unsigned xb_add(unsigned* p, unsigned v) { return __hip_atomic_fetch_add(p, v, __ATOMIC_RELAXED, __HIP_MEMORY_SCOPE_AGENT); }
; #define XB_SPIN(cond, bar) do { unsigned _sp = 0; while (cond) { __builtin_amdgcn_s_sleep(1); \
;     if ((++_sp & 255u) == 0u) { if (xb_ld(&(bar)[XB_TMO])) break; if (_sp > XB_SPIN_CAP) { atomicAdd(&(bar)[XB_TMO], 1u); break; } } } } while (0)
; __device__ __forceinline__ void xcd_barrier(const XcdBarrier& b) {
;     ...
;             __builtin_amdgcn_fence(__ATOMIC_RELEASE, "agent");
;             asm volatile("s_waitcnt vmcnt(0)" ::: "memory");
;             const unsigned og = xb_add(&bar[XB_TOP], 1u);
;             const unsigned tg = og / nx;
;             if (og + 1u == (tg + 1u) * nx) xb_add(&bar[XB_TOPGEN], 1u);
;             else XB_SPIN(xb_ld(&bar[XB_TOPGEN]) == tg, bar);
;             __builtin_amdgcn_fence(__ATOMIC_ACQUIRE, "agent");
;             xb_add(&bar[XB_XGEN(b.x)], 1u);
;             asm volatile("s_waitcnt vmcnt(0)" ::: "memory");
.LBB0_2195:
	s_or_b64 exec, exec, s[4:5]
	s_mov_b64 s[4:5], exec
	v_mbcnt_lo_u32_b32 v0, s4, 0
	v_mbcnt_hi_u32_b32 v0, s5, v0
	v_cmp_eq_u32_e32 vcc, 0, v0
	s_nop 0
	buffer_inv sc1
	s_and_saveexec_b64 s[6:7], vcc
	s_cbranch_execz .LBB0_2197
	s_bcnt1_i32_b64 s4, s[4:5]
	v_mov_b32_e32 v0, 0x2000
	v_mov_b32_e32 v1, s4
	s_nop 0
	s_nop 0
.LBB0_2197:
	s_or_b64 exec, exec, s[6:7]
	s_nop 0
